# grid-barrier release: with all 8 XCDs active the leader issues its 8 flag atomics back to back (global, one address setup) instead of 16 masked blocks
# speedup vs baseline: 1.0027x; 1.0027x over previous
; __device__ __forceinline__ unsigned xb_add(unsigned* p, unsigned v) { return __hip_atomic_fetch_add(p, v, __ATOMIC_RELAXED, __HIP_MEMORY_SCOPE_AGENT); }
; __device__ __forceinline__ void xcd_barrier(const XcdBarrier& b) {
;     ...
;         const unsigned old = xb_add(&bar[XB_XSUB(bx_)], 1u);
;         const unsigned gen = old / nloc;
;         if (old + 1u == (gen + 1u) * nloc) {
;             __builtin_amdgcn_fence(__ATOMIC_RELEASE, "agent");
;             asm volatile("s_waitcnt vmcnt(0)" ::: "memory");
; #pragma unroll
;             for (unsigned j = 0; j < 16; ++j) if ((xmask >> j) & 1u) (void)xb_add(&bar[XB_XGEN(j)], 1u);
.LBB0_697:
	s_lshl_b32 s4, s36, 6
	s_add_i32 s84, s4, 0x500
	s_lshl_b64 s[0:1], s[84:85], 2
	s_add_u32 s0, s34, s0
	s_addc_u32 s1, s35, s1
	v_mov_b64_e32 v[8:9], s[0:1]
	v_mov_b32_e32 v5, 1
	flat_atomic_add v5, v[8:9], v5 sc0
	v_cvt_f32_u32_e32 v7, v6
	v_sub_u32_e32 v8, 0, v6
	v_rcp_iflag_f32_e32 v7, v7
	s_nop 0
	v_mul_f32_e32 v7, 0x4f7ffffe, v7
	v_cvt_u32_f32_e32 v7, v7
	v_mul_lo_u32 v8, v8, v7
	v_mul_hi_u32 v8, v7, v8
	v_add_u32_e32 v7, v7, v8
	s_waitcnt vmcnt(0) lgkmcnt(0)
	v_mul_hi_u32 v7, v5, v7
	v_mul_lo_u32 v8, v7, v6
	v_sub_u32_e32 v8, v5, v8
	v_add_u32_e32 v9, 1, v7
	v_cmp_ge_u32_e32 vcc, v8, v6
	s_nop 1
	v_cndmask_b32_e32 v7, v7, v9, vcc
	v_sub_u32_e32 v9, v8, v6
	v_cndmask_b32_e32 v8, v8, v9, vcc
	v_add_u32_e32 v9, 1, v7
	v_cmp_ge_u32_e32 vcc, v8, v6
	v_add_u32_e32 v8, 1, v5
	s_nop 0
	v_cndmask_b32_e32 v7, v7, v9, vcc
	v_add_u32_e32 v5, 1, v7
	v_mul_lo_u32 v6, v5, v6
	v_cmp_eq_u32_e32 vcc, v8, v6
	s_and_saveexec_b64 s[0:1], vcc
	s_cbranch_execz .LBB0_730
	buffer_wbl2 sc1
	s_waitcnt vmcnt(0)
	v_cmp_eq_u32_e32 vcc, 0xff, v4
	s_cbranch_vccz .Lrf0_slow
	v_mov_b32_e32 v6, s34
	v_add_co_u32_e32 v6, vcc, 0x2000, v6
	v_mov_b32_e32 v7, s35
	s_nop 0
	v_addc_co_u32_e32 v7, vcc, 0, v7, vcc
	v_mov_b32_e32 v8, 1
	global_atomic_add v[6:7], v8, off offset:1024
	global_atomic_add v[6:7], v8, off offset:1280
	global_atomic_add v[6:7], v8, off offset:1536
	global_atomic_add v[6:7], v8, off offset:1792
	global_atomic_add v[6:7], v8, off offset:2048
	global_atomic_add v[6:7], v8, off offset:2304
	global_atomic_add v[6:7], v8, off offset:2560
	global_atomic_add v[6:7], v8, off offset:2816
	s_or_b64 exec, exec, s[0:1]
	s_branch .Lrf0_join
.Lrf0_slow:
	v_and_b32_e32 v6, 1, v4
	v_cmp_eq_u32_e32 vcc, 1, v6
	s_and_saveexec_b64 s[2:3], vcc
	s_cbranch_execz .LBB0_700
	v_mov_b32_e32 v6, s34
	v_add_co_u32_e32 v6, vcc, 0x2000, v6
	v_mov_b32_e32 v7, s35
	s_nop 0
	v_addc_co_u32_e32 v7, vcc, 0, v7, vcc
	v_mov_b32_e32 v8, 1
	flat_atomic_add v[6:7], v8 offset:1024

; __device__ __forceinline__ unsigned xb_ld(unsigned* p)              { return __hip_atomic_load(p, __ATOMIC_RELAXED, __HIP_MEMORY_SCOPE_AGENT); }
; __device__ __forceinline__ unsigned xb_add(unsigned* p, unsigned v) { return __hip_atomic_fetch_add(p, v, __ATOMIC_RELAXED, __HIP_MEMORY_SCOPE_AGENT); }
; #define XB_SPIN(cond, bar) do { unsigned _sp = 0; while (cond) { __builtin_amdgcn_s_sleep(1); \
;     if ((++_sp & 255u) == 0u) { if (xb_ld(&(bar)[XB_TMO])) break; if (_sp > XB_SPIN_CAP) { atomicAdd(&(bar)[XB_TMO], 1u); break; } } } } while (0)
; __device__ __forceinline__ void xcd_barrier(const XcdBarrier& b) {
;     ...
;             __builtin_amdgcn_fence(__ATOMIC_RELEASE, "agent");
;             asm volatile("s_waitcnt vmcnt(0)" ::: "memory");
; #pragma unroll
;             for (unsigned j = 0; j < 16; ++j) if ((xmask >> j) & 1u) (void)xb_add(&bar[XB_XGEN(j)], 1u);
;         }
;         XB_SPIN(xb_ld(&bar[XB_XGEN(bx_)]) < (gen + 1u) * nx, bar);
.LBB0_730:
	s_or_b64 exec, exec, s[0:1]
	s_waitcnt vmcnt(0) lgkmcnt(0)
.Lrf0_join:
	s_add_i32 s84, s4, 0x900
	s_lshl_b64 s[0:1], s[84:85], 2
	s_add_u32 s0, s34, s0
	s_addc_u32 s1, s35, s1
	v_mul_lo_u32 v2, v5, v2
	v_mov_b64_e32 v[4:5], s[0:1]
	s_movk_i32 s2, 0x1000
	global_load_dword v6, v[4:5], off sc1
	s_sleep 10
	global_load_dword v7, v[4:5], off sc1
	s_sleep 10
	global_load_dword v8, v[4:5], off sc1
